# pvprio_s + up GEMM unit order with row-panel group 4 instead of 8 (pre-pass and unit-loop decode patched consistently)
# speedup vs baseline: 1.0080x; 1.0004x over previous
;     __device__ bool next(int i, Unit& u) const {
;         const long L = (long)i * G + c; if (L >= nwg) return false;
;         int wgid = (int)L; { const int q = nwg / NXCD, r = nwg % NXCD, xcd = wgid % NXCD, off = wgid / NXCD; wgid = (xcd < r ? xcd * (q + 1) : r * (q + 1) + (xcd - r) * q) + off; }
;         const int nig = wgm * nN, gid = wgid / nig, fm = gid * wgm, gsz = (nM - fm) < wgm ? (nM - fm) : wgm;
;         u.pm = fm + ((wgid % nig) % gsz); u.pn = (wgid % nig) / gsz; if (rev) u.pm = nM - 1 - u.pm; return true;
; __global__ void __launch_bounds__(NWAVES * 64, 2) fwd_kernel(Args args) {
;     ...
;             { pg8::Unit u; for (int i = wave >> 2; S.next(i, u); i += 2)       { const int row = tid & 255; const int ai = row >> 7, wr = (row >> 6) & 1, m = (row >> 4) & 3, fr = row & 15;
;                 const int pp = UPM * u.pm - 1 + 126 * wr + 8 * fr + 4 * ai + m;
;                 const int tok = min(max(pp - (pp > SEQ ? 1 : 0) - (pp > 2 * SEQ + 1 ? 1 : 0), 0), M - 1);
;                 const float* p = SSX + (size_t)tok * 16;
;                 const f32x4 a = *(const f32x4*)p, b = *(const f32x4*)(p + 4), c = *(const f32x4*)(p + 8), d = *(const f32x4*)(p + 12);
.LBB0_522:
	v_readlane_b32 s12, v255, 2
	v_readlane_b32 s13, v255, 3
	s_xor_b64 s[22:23], s[12:13], -1
	s_xor_b64 s[24:25], s[88:89], -1
	v_readlane_b32 s14, v252, 3
	v_readlane_b32 s15, v252, 4
	s_cmp_le_i32 s14, s5
	s_cselect_b64 s[12:13], -1, 0
	s_cmp_lt_i32 s5, s15
	s_cselect_b64 s[14:15], -1, 0
	s_and_b64 s[34:35], s[12:13], s[14:15]
	s_andn2_b64 vcc, exec, s[34:35]
	s_cbranch_vccnz .LBB0_619
	v_mbcnt_lo_u32_b32 v0, -1, 0
	v_mbcnt_hi_u32_b32 v0, -1, v0
	v_readlane_b32 s0, v252, 43
	v_readlane_b32 s18, v254, 48
	v_readlane_b32 s5, v254, 51
	s_nop 0
	v_add_u32_e32 v0, s0, v0
	v_and_b32_e32 v2, 0xff, v0
	v_bfe_u32 v3, v0, 4, 2
	v_bfe_i32 v4, v0, 6, 1
	v_lshlrev_b32_e32 v5, 3, v0
	v_lshrrev_b32_e32 v0, 5, v0
	v_and_b32_e32 v5, 0x78, v5
	v_and_b32_e32 v0, 4, v0
	v_and_b32_e32 v4, 0x7e, v4
	v_or3_b32 v0, v5, v0, v3
	v_add3_u32 v0, v0, v4, -1
	v_lshl_add_u32 v2, v2, 2, s5
	v_mov_b32_e32 v175, 0xbfff
	s_mov_b32 s10, 0
	s_cmpk_lt_u32 s18, 0x10d8
	s_cbranch_scc0 .Lupre_issued
	s_and_b32 s12, s18, 7
	s_lshr_b32 s13, s18, 3
	s_mulk_i32 s12, 0x21b
	s_add_i32 s12, s12, s13
	s_lshr_b32 s13, s12, 3
	s_mul_hi_u32 s13, s13, 0xba2e8ba3
	s_lshr_b32 s13, s13, 3
	s_mul_i32 s14, s13, 0x58
	s_sub_i32 s12, s12, s14
	s_lshl_b32 s13, s13, 2
	s_sub_i32 s14, 0xc4, s13
	s_min_u32 s14, s14, 4
	s_sub_i32 s14, s14, 1
	s_and_b32 s12, s12, s14
	s_add_i32 s12, s13, s12
	s_mulk_i32 s12, 0xfc
	v_add_u32_e32 v166, s12, v0
	v_cmp_lt_i32_e32 vcc, 0x4000, v166
	s_nop 1
	v_subbrev_co_u32_e32 v3, vcc, 0, v166, vcc
	v_cmp_lt_i32_e32 vcc, 0x8001, v166
	s_nop 1
	v_subbrev_co_u32_e32 v3, vcc, 0, v3, vcc
	v_med3_i32 v3, v3, 0, v175
	v_lshlrev_b32_e32 v3, 6, v3
	global_load_dwordx4 v[22:25], v3, s[28:29] offset:48
	global_load_dwordx4 v[26:29], v3, s[28:29] offset:32
	global_load_dwordx4 v[30:33], v3, s[28:29] offset:16
	global_load_dwordx4 v[34:37], v3, s[28:29]
	s_add_u32 s18, s18, s74
	s_add_i32 s10, s10, 1
	s_cmpk_lt_u32 s18, 0x10d8
	s_cbranch_scc0 .Lupre_issued
	s_and_b32 s12, s18, 7
	s_lshr_b32 s13, s18, 3
	s_mulk_i32 s12, 0x21b
	s_add_i32 s12, s12, s13
	s_lshr_b32 s13, s12, 3
	s_mul_hi_u32 s13, s13, 0xba2e8ba3
	s_lshr_b32 s13, s13, 3
	s_mul_i32 s14, s13, 0x58
	s_sub_i32 s12, s12, s14
	s_lshl_b32 s13, s13, 2
	s_sub_i32 s14, 0xc4, s13
	s_min_u32 s14, s14, 4
	s_sub_i32 s14, s14, 1
	s_and_b32 s12, s12, s14
	s_add_i32 s12, s13, s12
	s_mulk_i32 s12, 0xfc
	v_add_u32_e32 v167, s12, v0
	v_cmp_lt_i32_e32 vcc, 0x4000, v167
	s_nop 1
	v_subbrev_co_u32_e32 v3, vcc, 0, v167, vcc
	v_cmp_lt_i32_e32 vcc, 0x8001, v167
	s_nop 1
	v_subbrev_co_u32_e32 v3, vcc, 0, v3, vcc
	v_med3_i32 v3, v3, 0, v175
	v_lshlrev_b32_e32 v3, 6, v3
	global_load_dwordx4 v[38:41], v3, s[28:29] offset:48
	global_load_dwordx4 v[42:45], v3, s[28:29] offset:32
	global_load_dwordx4 v[46:49], v3, s[28:29] offset:16
	global_load_dwordx4 v[50:53], v3, s[28:29]
	s_add_u32 s18, s18, s74
	s_add_i32 s10, s10, 1
	s_cmpk_lt_u32 s18, 0x10d8
	s_cbranch_scc0 .Lupre_issued
	s_and_b32 s12, s18, 7
	s_lshr_b32 s13, s18, 3
	s_mulk_i32 s12, 0x21b
	s_add_i32 s12, s12, s13
	s_lshr_b32 s13, s12, 3
	s_mul_hi_u32 s13, s13, 0xba2e8ba3
	s_lshr_b32 s13, s13, 3
	s_mul_i32 s14, s13, 0x58
	s_sub_i32 s12, s12, s14
	s_lshl_b32 s13, s13, 2
	s_sub_i32 s14, 0xc4, s13
	s_min_u32 s14, s14, 4
	s_sub_i32 s14, s14, 1
	s_and_b32 s12, s12, s14
	s_add_i32 s12, s13, s12
	s_mulk_i32 s12, 0xfc
	v_add_u32_e32 v168, s12, v0
	v_cmp_lt_i32_e32 vcc, 0x4000, v168
	s_nop 1
	v_subbrev_co_u32_e32 v3, vcc, 0, v168, vcc
	v_cmp_lt_i32_e32 vcc, 0x8001, v168
	s_nop 1
	v_subbrev_co_u32_e32 v3, vcc, 0, v3, vcc
	v_med3_i32 v3, v3, 0, v175
	v_lshlrev_b32_e32 v3, 6, v3
	global_load_dwordx4 v[54:57], v3, s[28:29] offset:48
	global_load_dwordx4 v[58:61], v3, s[28:29] offset:32
	global_load_dwordx4 v[62:65], v3, s[28:29] offset:16
	global_load_dwordx4 v[66:69], v3, s[28:29]
	s_add_u32 s18, s18, s74
	s_add_i32 s10, s10, 1
	s_cmpk_lt_u32 s18, 0x10d8
	s_cbranch_scc0 .Lupre_issued
	s_and_b32 s12, s18, 7
	s_lshr_b32 s13, s18, 3
	s_mulk_i32 s12, 0x21b
	s_add_i32 s12, s12, s13
	s_lshr_b32 s13, s12, 3
	s_mul_hi_u32 s13, s13, 0xba2e8ba3
	s_lshr_b32 s13, s13, 3
	s_mul_i32 s14, s13, 0x58
	s_sub_i32 s12, s12, s14
	s_lshl_b32 s13, s13, 2
	s_sub_i32 s14, 0xc4, s13
	s_min_u32 s14, s14, 4
	s_sub_i32 s14, s14, 1
	s_and_b32 s12, s12, s14
	s_add_i32 s12, s13, s12
	s_mulk_i32 s12, 0xfc
	v_add_u32_e32 v169, s12, v0
	v_cmp_lt_i32_e32 vcc, 0x4000, v169
	s_nop 1
	v_subbrev_co_u32_e32 v3, vcc, 0, v169, vcc
	v_cmp_lt_i32_e32 vcc, 0x8001, v169
	s_nop 1
	v_subbrev_co_u32_e32 v3, vcc, 0, v3, vcc
	v_med3_i32 v3, v3, 0, v175
	v_lshlrev_b32_e32 v3, 6, v3
	global_load_dwordx4 v[70:73], v3, s[28:29] offset:48
	global_load_dwordx4 v[74:77], v3, s[28:29] offset:32
	global_load_dwordx4 v[78:81], v3, s[28:29] offset:16
	global_load_dwordx4 v[82:85], v3, s[28:29]
	s_add_u32 s18, s18, s74
	s_add_i32 s10, s10, 1
	s_cmpk_lt_u32 s18, 0x10d8
	s_cbranch_scc0 .Lupre_issued
;     __device__ bool next(int i, Unit& u) const {
;         const long L = (long)i * G + c; if (L >= nwg) return false;
;         int wgid = (int)L; { const int q = nwg / NXCD, r = nwg % NXCD, xcd = wgid % NXCD, off = wgid / NXCD; wgid = (xcd < r ? xcd * (q + 1) : r * (q + 1) + (xcd - r) * q) + off; }
;         const int nig = wgm * nN, gid = wgid / nig, fm = gid * wgm, gsz = (nM - fm) < wgm ? (nM - fm) : wgm;
;         u.pm = fm + ((wgid % nig) % gsz); u.pn = (wgid % nig) / gsz; if (rev) u.pm = nM - 1 - u.pm; return true;
; __global__ void __launch_bounds__(NWAVES * 64, 2) fwd_kernel(Args args) {
;     ...
;             { pg8::Unit u; for (int i = wave >> 2; S.next(i, u); i += 2)       { const int row = tid & 255; const int ai = row >> 7, wr = (row >> 6) & 1, m = (row >> 4) & 3, fr = row & 15;
;                 const int pp = UPM * u.pm - 1 + 126 * wr + 8 * fr + 4 * ai + m;
;                 const int tok = min(max(pp - (pp > SEQ ? 1 : 0) - (pp > 2 * SEQ + 1 ? 1 : 0), 0), M - 1);
;                 const float* p = SSX + (size_t)tok * 16;
;                 const f32x4 a = *(const f32x4*)p, b = *(const f32x4*)(p + 4), c = *(const f32x4*)(p + 8), d = *(const f32x4*)(p + 12);
	s_and_b32 s12, s18, 7
	s_lshr_b32 s13, s18, 3
	s_mulk_i32 s12, 0x21b
	s_add_i32 s12, s12, s13
	s_lshr_b32 s13, s12, 3
	s_mul_hi_u32 s13, s13, 0xba2e8ba3
	s_lshr_b32 s13, s13, 3
	s_mul_i32 s14, s13, 0x58
	s_sub_i32 s12, s12, s14
	s_lshl_b32 s13, s13, 2
	s_sub_i32 s14, 0xc4, s13
	s_min_u32 s14, s14, 4
	s_sub_i32 s14, s14, 1
	s_and_b32 s12, s12, s14
	s_add_i32 s12, s13, s12
	s_mulk_i32 s12, 0xfc
	v_add_u32_e32 v170, s12, v0
	v_cmp_lt_i32_e32 vcc, 0x4000, v170
	s_nop 1
	v_subbrev_co_u32_e32 v3, vcc, 0, v170, vcc
	v_cmp_lt_i32_e32 vcc, 0x8001, v170
	s_nop 1
	v_subbrev_co_u32_e32 v3, vcc, 0, v3, vcc
	v_med3_i32 v3, v3, 0, v175
	v_lshlrev_b32_e32 v3, 6, v3
	global_load_dwordx4 v[86:89], v3, s[28:29] offset:48
	global_load_dwordx4 v[90:93], v3, s[28:29] offset:32
	global_load_dwordx4 v[94:97], v3, s[28:29] offset:16
	global_load_dwordx4 v[98:101], v3, s[28:29]
	s_add_u32 s18, s18, s74
	s_add_i32 s10, s10, 1
	s_cmpk_lt_u32 s18, 0x10d8
	s_cbranch_scc0 .Lupre_issued
	s_and_b32 s12, s18, 7
	s_lshr_b32 s13, s18, 3
	s_mulk_i32 s12, 0x21b
	s_add_i32 s12, s12, s13
	s_lshr_b32 s13, s12, 3
	s_mul_hi_u32 s13, s13, 0xba2e8ba3
	s_lshr_b32 s13, s13, 3
	s_mul_i32 s14, s13, 0x58
	s_sub_i32 s12, s12, s14
	s_lshl_b32 s13, s13, 2
	s_sub_i32 s14, 0xc4, s13
	s_min_u32 s14, s14, 4
	s_sub_i32 s14, s14, 1
	s_and_b32 s12, s12, s14
	s_add_i32 s12, s13, s12
	s_mulk_i32 s12, 0xfc
	v_add_u32_e32 v171, s12, v0
	v_cmp_lt_i32_e32 vcc, 0x4000, v171
	s_nop 1
	v_subbrev_co_u32_e32 v3, vcc, 0, v171, vcc
	v_cmp_lt_i32_e32 vcc, 0x8001, v171
	s_nop 1
	v_subbrev_co_u32_e32 v3, vcc, 0, v3, vcc
	v_med3_i32 v3, v3, 0, v175
	v_lshlrev_b32_e32 v3, 6, v3
	global_load_dwordx4 v[102:105], v3, s[28:29] offset:48
	global_load_dwordx4 v[106:109], v3, s[28:29] offset:32
	global_load_dwordx4 v[110:113], v3, s[28:29] offset:16
	global_load_dwordx4 v[114:117], v3, s[28:29]
	s_add_u32 s18, s18, s74
	s_add_i32 s10, s10, 1
	s_cmpk_lt_u32 s18, 0x10d8
	s_cbranch_scc0 .Lupre_issued
	s_and_b32 s12, s18, 7
	s_lshr_b32 s13, s18, 3
	s_mulk_i32 s12, 0x21b
	s_add_i32 s12, s12, s13
	s_lshr_b32 s13, s12, 3
	s_mul_hi_u32 s13, s13, 0xba2e8ba3
	s_lshr_b32 s13, s13, 3
	s_mul_i32 s14, s13, 0x58
	s_sub_i32 s12, s12, s14
	s_lshl_b32 s13, s13, 2
	s_sub_i32 s14, 0xc4, s13
	s_min_u32 s14, s14, 4
	s_sub_i32 s14, s14, 1
	s_and_b32 s12, s12, s14
	s_add_i32 s12, s13, s12
	s_mulk_i32 s12, 0xfc
	v_add_u32_e32 v172, s12, v0
	v_cmp_lt_i32_e32 vcc, 0x4000, v172
	s_nop 1
	v_subbrev_co_u32_e32 v3, vcc, 0, v172, vcc
	v_cmp_lt_i32_e32 vcc, 0x8001, v172
	s_nop 1
	v_subbrev_co_u32_e32 v3, vcc, 0, v3, vcc
	v_med3_i32 v3, v3, 0, v175
	v_lshlrev_b32_e32 v3, 6, v3
	global_load_dwordx4 v[118:121], v3, s[28:29] offset:48
	global_load_dwordx4 v[122:125], v3, s[28:29] offset:32
	global_load_dwordx4 v[126:129], v3, s[28:29] offset:16
	global_load_dwordx4 v[130:133], v3, s[28:29]
	s_add_u32 s18, s18, s74
	s_add_i32 s10, s10, 1
	s_cmpk_lt_u32 s18, 0x10d8
	s_cbranch_scc0 .Lupre_issued
	s_and_b32 s12, s18, 7
	s_lshr_b32 s13, s18, 3
	s_mulk_i32 s12, 0x21b
	s_add_i32 s12, s12, s13
	s_lshr_b32 s13, s12, 3
	s_mul_hi_u32 s13, s13, 0xba2e8ba3
	s_lshr_b32 s13, s13, 3
	s_mul_i32 s14, s13, 0x58
	s_sub_i32 s12, s12, s14
	s_lshl_b32 s13, s13, 2
	s_sub_i32 s14, 0xc4, s13
	s_min_u32 s14, s14, 4
	s_sub_i32 s14, s14, 1
	s_and_b32 s12, s12, s14
	s_add_i32 s12, s13, s12
	s_mulk_i32 s12, 0xfc
	v_add_u32_e32 v173, s12, v0
	v_cmp_lt_i32_e32 vcc, 0x4000, v173
	s_nop 1
	v_subbrev_co_u32_e32 v3, vcc, 0, v173, vcc
	v_cmp_lt_i32_e32 vcc, 0x8001, v173
	s_nop 1
	v_subbrev_co_u32_e32 v3, vcc, 0, v3, vcc
	v_med3_i32 v3, v3, 0, v175
	v_lshlrev_b32_e32 v3, 6, v3
	global_load_dwordx4 v[134:137], v3, s[28:29] offset:48
	global_load_dwordx4 v[138:141], v3, s[28:29] offset:32
	global_load_dwordx4 v[142:145], v3, s[28:29] offset:16
	global_load_dwordx4 v[146:149], v3, s[28:29]
	s_add_u32 s18, s18, s74
	s_add_i32 s10, s10, 1
	s_cmpk_lt_u32 s18, 0x10d8
	s_cbranch_scc0 .Lupre_issued
	s_and_b32 s12, s18, 7
	s_lshr_b32 s13, s18, 3
	s_mulk_i32 s12, 0x21b
	s_add_i32 s12, s12, s13
	s_lshr_b32 s13, s12, 3
	s_mul_hi_u32 s13, s13, 0xba2e8ba3
	s_lshr_b32 s13, s13, 3
	s_mul_i32 s14, s13, 0x58
	s_sub_i32 s12, s12, s14
	s_lshl_b32 s13, s13, 2
	s_sub_i32 s14, 0xc4, s13
	s_min_u32 s14, s14, 4
	s_sub_i32 s14, s14, 1
	s_and_b32 s12, s12, s14
	s_add_i32 s12, s13, s12
	s_mulk_i32 s12, 0xfc
	v_add_u32_e32 v174, s12, v0
	v_cmp_lt_i32_e32 vcc, 0x4000, v174
	s_nop 1
	v_subbrev_co_u32_e32 v3, vcc, 0, v174, vcc
	v_cmp_lt_i32_e32 vcc, 0x8001, v174
	s_nop 1
	v_subbrev_co_u32_e32 v3, vcc, 0, v3, vcc
	v_med3_i32 v3, v3, 0, v175
	v_lshlrev_b32_e32 v3, 6, v3
	global_load_dwordx4 v[150:153], v3, s[28:29] offset:48
	global_load_dwordx4 v[154:157], v3, s[28:29] offset:32
	global_load_dwordx4 v[158:161], v3, s[28:29] offset:16
	global_load_dwordx4 v[162:165], v3, s[28:29]
	s_add_u32 s18, s18, s74
	s_add_i32 s10, s10, 1

;     __device__ bool next(int i, Unit& u) const {
;         const long L = (long)i * G + c; if (L >= nwg) return false;
;         int wgid = (int)L; { const int q = nwg / NXCD, r = nwg % NXCD, xcd = wgid % NXCD, off = wgid / NXCD; wgid = (xcd < r ? xcd * (q + 1) : r * (q + 1) + (xcd - r) * q) + off; }
;         const int nig = wgm * nN, gid = wgid / nig, fm = gid * wgm, gsz = (nM - fm) < wgm ? (nM - fm) : wgm;
;         u.pm = fm + ((wgid % nig) % gsz); u.pn = (wgid % nig) / gsz; if (rev) u.pm = nM - 1 - u.pm; return true;
; template <class Epi, bool ALIGN_EPI, bool EARLY_DRAIN = true, class Pre = NoPre>
; __device__ __forceinline__ void gemm_phase(LAS unsigned char* lds, const Gemm g, const StaticOrder& S, const Epi& E, int wv, const Pre& pre = Pre()) {
;     ...
;     if (!S.next(0, cur)) return;
; __global__ void __launch_bounds__(NWAVES * 64, 2) fwd_kernel(Args args) {
;     ...
;             __syncthreads();
.Lupre_done:
.LBB0_537:
	v_readlane_b32 s12, v254, 13
	s_waitcnt lgkmcnt(0)
	s_barrier
	v_mbcnt_lo_u32_b32 v0, -1, 0
	v_mbcnt_hi_u32_b32 v0, -1, v0
	v_readlane_b32 s0, v252, 43
	v_readlane_b32 s13, v254, 14
	s_andn2_b64 vcc, exec, s[12:13]
	v_add_u32_e32 v2, s0, v0
	v_cndmask_b32_e64 v0, 0, 1, s[12:13]
	v_cmp_ne_u32_e64 s[38:39], 1, v0
	v_readfirstlane_b32 s0, v2
	s_cbranch_vccnz .LBB0_539
	v_readlane_b32 s5, v254, 50
	s_mov_b32 s46, s5
	v_readlane_b32 s99, v254, 47
	s_and_b32 s5, s2, 7
	s_lshr_b32 s14, s2, 3
	s_mulk_i32 s5, 0x21b
	s_add_i32 s5, s5, s14
	s_lshr_b32 s14, s5, 3
	s_mul_hi_u32 s14, s14, 0xba2e8ba3
	s_lshr_b32 s14, s14, 3
	s_mul_i32 s15, s14, 88
	s_sub_i32 s5, s5, s15
	s_lshl_b32 s14, s14, 2
	s_sub_i32 s15, 0xc4, s14
	s_min_u32 s15, s15, 4
	s_sub_i32 s101, s15, 1
	s_and_b32 s101, s5, s101
	s_add_i32 s99, s14, s101
	s_ff1_i32_b32 s15, s15
	s_lshr_b32 s46, s5, s15

;     __device__ bool next(int i, Unit& u) const {
;         const long L = (long)i * G + c; if (L >= nwg) return false;
;         int wgid = (int)L; { const int q = nwg / NXCD, r = nwg % NXCD, xcd = wgid % NXCD, off = wgid / NXCD; wgid = (xcd < r ? xcd * (q + 1) : r * (q + 1) + (xcd - r) * q) + off; }
;         const int nig = wgm * nN, gid = wgid / nig, fm = gid * wgm, gsz = (nM - fm) < wgm ? (nM - fm) : wgm;
;         u.pm = fm + ((wgid % nig) % gsz); u.pn = (wgid % nig) / gsz; if (rev) u.pm = nM - 1 - u.pm; return true;
; template <class Epi, bool ALIGN_EPI, bool EARLY_DRAIN = true, class Pre = NoPre>
; __device__ __forceinline__ void gemm_phase(LAS unsigned char* lds, const Gemm g, const StaticOrder& S, const Epi& E, int wv, const Pre& pre = Pre()) {
;     ...
;         const bool has_next = S.next(ui + 1, nxt);
;         const char* nA = has_next ? g.A + (size_t)nxt.pm * g.a_tstep + (size_t)(nxt.pm >> 6) * g.a_pad : cA; const char* nB = has_next ? g.Bt + (size_t)nxt.pn * g.b_tstep : cB;
.LBB0_547:
	s_add_i32 s27, s17, 1
	s_mul_i32 s14, s27, s73
	s_mul_hi_u32 s15, s27, s72
	s_add_i32 s15, s15, s14
	s_mul_i32 s14, s27, s72
	s_add_u32 s38, s14, s2
	s_addc_u32 s39, s15, s3
	v_mov_b64_e32 v[2:3], 0x10d8
	v_cmp_lt_i64_e64 s[40:41], s[38:39], v[2:3]
	v_mov_b64_e32 v[2:3], 0x10d7
	v_cmp_gt_i64_e32 vcc, s[38:39], v[2:3]
	s_cbranch_vccnz .LBB0_549
	s_mov_b32 s101, s38
	s_ashr_i32 s14, s38, 31
	s_lshr_b32 s14, s14, 29
	s_add_i32 s14, s38, s14
	s_ashr_i32 s15, s14, 3
	s_and_b32 s14, s14, -8
	s_sub_i32 s14, s38, s14
	s_cmp_lt_i32 s14, 0
	s_movk_i32 s16, 0x21c
	s_cselect_b32 s16, s16, 0x21b
	s_mul_i32 s14, s14, s16
	s_add_i32 s14, s14, s15
	s_mul_hi_i32 s15, s14, 0x2e8ba2e9
	s_lshr_b32 s16, s15, 31
	s_ashr_i32 s15, s15, 5
	s_add_i32 s15, s15, s16
	s_lshl_b32 s16, s15, 3
	s_sub_i32 s38, 0xc4, s16
	s_min_i32 s38, s38, 8
	s_abs_i32 s39, s38
	v_cvt_f32_u32_e32 v0, s39
	s_sub_i32 s43, 0, s39
	s_mulk_i32 s15, 0xb0
	s_sub_i32 s14, s14, s15
	v_rcp_iflag_f32_e32 v0, v0
	s_abs_i32 s15, s14
	s_xor_b32 s42, s14, s38
	s_ashr_i32 s42, s42, 31
	v_mul_f32_e32 v0, 0x4f7ffffe, v0
	v_cvt_u32_f32_e32 v0, v0
	s_nop 0
	v_readfirstlane_b32 s47, v0
	s_mul_i32 s43, s43, s47
	s_mul_hi_u32 s43, s47, s43
	s_add_i32 s47, s47, s43
	s_mul_hi_u32 s43, s15, s47
	s_mul_i32 s47, s43, s39
	s_sub_i32 s15, s15, s47
	s_add_i32 s50, s43, 1
	s_sub_i32 s47, s15, s39
	s_cmp_ge_u32 s15, s39
	s_cselect_b32 s43, s50, s43
	s_cselect_b32 s15, s47, s15
	s_add_i32 s47, s43, 1
	s_cmp_ge_u32 s15, s39
	s_cselect_b32 s15, s47, s43
	s_xor_b32 s15, s15, s42
	s_sub_i32 s60, s15, s42
	s_mul_i32 s15, s60, s38
	s_sub_i32 s14, s14, s15
	s_add_i32 s16, s16, s14
	s_and_b32 s14, s101, 7
	s_lshr_b32 s15, s101, 3
	s_mulk_i32 s14, 0x21b
	s_add_i32 s14, s14, s15
	s_lshr_b32 s15, s14, 3
	s_mul_hi_u32 s15, s15, 0xba2e8ba3
	s_lshr_b32 s15, s15, 3
	s_mul_i32 s38, s15, 88
	s_sub_i32 s14, s14, s38
	s_lshl_b32 s15, s15, 2
	s_sub_i32 s38, 0xc4, s15
	s_min_u32 s38, s38, 4
	s_sub_i32 s39, s38, 1
	s_and_b32 s39, s14, s39
	s_add_i32 s16, s15, s39
	s_ff1_i32_b32 s38, s38
	s_lshr_b32 s60, s14, s38
